# P0 rmsnorm row loop: next row loads prefetched into a second register set
# baseline (speedup 1.0000x reference)
; __device__ __forceinline__ void p0_prologue(const Args& A, LAS unsigned char* lds, int vcu, int G) {
;     ...
;     bf16* XN = (bf16*)(ws + WS_XN);
;     f32x4 gv[4];
; #pragma unroll
;     for (int j = 0; j < 4; ++j) gv[j] = ((const f32x4*)A.g_mix)[lane + 64 * j];
;     for (int m = gw; m < M; m += NGW) {
;         const f32x4* xr = (const f32x4*)(A.x + (size_t)m * DM) + lane;
;         f32x4 v[4]; float s = 0.f;
; #pragma unroll
;         for (int j = 0; j < 4; ++j) { v[j] = xr[64 * j]; s += (v[j].x * v[j].x + v[j].y * v[j].y) + (v[j].z * v[j].z + v[j].w * v[j].w); }
.LBB0_78:
	s_or_b64 exec, exec, s[14:15]
	s_mov_b32 s0, 0x10000
	v_cmp_gt_i32_e32 vcc, s0, v16
	s_and_saveexec_b64 s[4:5], vcc
	s_cbranch_execz .LBB0_81
	v_lshlrev_b32_e32 v28, 4, v42
	s_waitcnt lgkmcnt(0)
	global_load_dwordx4 v[0:3], v28, s[48:49] offset:3072
	global_load_dwordx4 v[4:7], v28, s[48:49] offset:2048
	global_load_dwordx4 v[8:11], v28, s[48:49] offset:1024
	global_load_dwordx4 v[12:15], v28, s[48:49]
	v_mbcnt_lo_u32_b32 v17, -1, 0
	v_mbcnt_hi_u32_b32 v17, -1, v17
	v_and_b32_e32 v18, 64, v17
	v_add_u32_e32 v18, 64, v18
	v_xor_b32_e32 v19, 1, v17
	v_cmp_lt_i32_e32 vcc, v19, v18
	s_mov_b64 s[0:1], 0x400
	s_ashr_i32 s13, s12, 31
	v_cndmask_b32_e32 v19, v17, v19, vcc
	v_lshlrev_b32_e32 v22, 2, v19
	v_xor_b32_e32 v19, 2, v17
	v_cmp_lt_i32_e32 vcc, v19, v18
	s_lshl_b64 s[6:7], s[12:13], 11
	s_lshl_b64 s[8:9], s[12:13], 12
	v_cndmask_b32_e32 v19, v17, v19, vcc
	v_lshlrev_b32_e32 v23, 2, v19
	v_xor_b32_e32 v19, 4, v17
	v_cmp_lt_i32_e32 vcc, v19, v18
	s_mov_b64 s[14:15], 0
	s_mov_b32 s3, 0xf800000
	v_cndmask_b32_e32 v19, v17, v19, vcc
	v_lshlrev_b32_e32 v24, 2, v19
	v_xor_b32_e32 v19, 8, v17
	v_cmp_lt_i32_e32 vcc, v19, v18
	s_mov_b32 s13, 0xffff
	s_nop 0
	v_cndmask_b32_e32 v19, v17, v19, vcc
	v_lshlrev_b32_e32 v25, 2, v19
	v_xor_b32_e32 v19, 16, v17
	v_cmp_lt_i32_e32 vcc, v19, v18
	s_nop 1
	v_cndmask_b32_e32 v19, v17, v19, vcc
	v_lshlrev_b32_e32 v26, 2, v19
	v_xor_b32_e32 v19, 32, v17
	v_cmp_lt_i32_e32 vcc, v19, v18
	s_nop 1
	v_cndmask_b32_e32 v17, v17, v19, vcc
	v_lshlrev_b32_e32 v27, 2, v17
	v_ashrrev_i32_e32 v17, 31, v16
	v_lshlrev_b64 v[18:19], 11, v[16:17]
	v_lshl_or_b32 v18, v42, 3, v18
	v_lshlrev_b64 v[20:21], 12, v[16:17]
	v_lshl_add_u64 v[18:19], s[76:77], 0, v[18:19]
	v_or_b32_e32 v20, v20, v28
	v_lshl_add_u64 v[18:19], v[18:19], 0, s[0:1]
	v_lshl_add_u64 v[20:21], s[60:61], 0, v[20:21]
	s_mov_b64 s[0:1], 0xc00
	v_lshl_add_u64 v[20:21], v[20:21], 0, s[0:1]
	v_mov_b32_e32 v17, 0x358637bd
	v_mov_b32_e32 v28, 0x260
	global_load_dwordx4 v[30:33], v[20:21], off offset:-3072
	global_load_dwordx4 v[34:37], v[20:21], off offset:-2048
	global_load_dwordx4 v[38:41], v[20:21], off offset:-1024
	global_load_dwordx4 v[42:45], v[20:21], off
	s_waitcnt vmcnt(0)
; __device__ __forceinline__ unsigned pk2(float lo, float hi) { f32x2 v = {lo, hi}; bf16x2_t b = __builtin_convertvector(v, bf16x2_t); return __builtin_bit_cast(unsigned, b); }
; __device__ __forceinline__ void p0_prologue(const Args& A, LAS unsigned char* lds, int vcu, int G) {
;     ...
;     for (int m = gw; m < M; m += NGW) {
;         const f32x4* xr = (const f32x4*)(A.x + (size_t)m * DM) + lane;
;         f32x4 v[4]; float s = 0.f;
; #pragma unroll
;         for (int j = 0; j < 4; ++j) { v[j] = xr[64 * j]; s += (v[j].x * v[j].x + v[j].y * v[j].y) + (v[j].z * v[j].z + v[j].w * v[j].w); }
;         const float rstd = 1.0f / sqrtf(wave_sum(s) * (1.0f / DM) + 1e-6f);
;         u32x2* o8 = (u32x2*)(XN + (size_t)m * DM) + lane;
; #pragma unroll
;         for (int j = 0; j < 4; ++j) { u32x2 w; w.x = pk2(v[j].x * rstd * gv[j].x, v[j].y * rstd * gv[j].y); w.y = pk2(v[j].z * rstd * gv[j].z, v[j].w * rstd * gv[j].w); o8[64 * j] = w; }
;     }
.LBB0_80:
	v_add_u32_e32 v16, s12, v16
	v_cmp_lt_i32_e32 vcc, s13, v16
	s_or_b64 s[14:15], vcc, s[14:15]
	v_lshl_add_u64 v[20:21], v[20:21], 0, s[8:9]
	s_mov_b64 s[0:1], exec
	s_andn2_b64 exec, exec, s[14:15]
	global_load_dwordx4 v[62:65], v[20:21], off offset:-3072
	global_load_dwordx4 v[66:69], v[20:21], off offset:-2048
	global_load_dwordx4 v[70:73], v[20:21], off offset:-1024
	global_load_dwordx4 v[74:77], v[20:21], off
	s_mov_b64 exec, s[0:1]
	v_pk_mul_f32 v[46:47], v[32:33], v[32:33]
	v_pk_mul_f32 v[48:49], v[30:31], v[30:31]
	v_pk_mul_f32 v[50:51], v[36:37], v[36:37]
	v_pk_mul_f32 v[52:53], v[34:35], v[34:35]
	v_pk_mov_b32 v[58:59], v[48:49], v[46:47] op_sel:[1,0]
	v_mov_b32_e32 v49, v47
	v_pk_mov_b32 v[46:47], v[52:53], v[50:51] op_sel:[1,0]
	v_mov_b32_e32 v53, v51
	v_mul_f32_e32 v57, v43, v43
	v_mul_f32_e32 v54, v39, v39
	v_mul_f32_e32 v56, v41, v41
	v_pk_add_f32 v[48:49], v[58:59], v[48:49]
	v_pk_add_f32 v[46:47], v[46:47], v[52:53]
	v_mul_f32_e32 v29, v42, v42
	v_mul_f32_e32 v60, v44, v44
	v_mul_f32_e32 v61, v45, v45
	v_pk_fma_f32 v[50:51], v[38:39], v[38:39], v[54:55] op_sel_hi:[1,1,0]
	v_pk_fma_f32 v[54:55], v[40:41], v[40:41], v[56:57] op_sel_hi:[1,1,0]
	v_pk_add_f32 v[48:49], v[48:49], v[48:49] op_sel:[0,1] op_sel_hi:[1,0]
	v_pk_add_f32 v[46:47], v[46:47], v[46:47] op_sel:[0,1] op_sel_hi:[1,0]
	v_mov_b32_e32 v51, v60
	v_mov_b32_e32 v55, v61
	v_mov_b32_e32 v49, v29
	v_mov_b32_e32 v47, v57
	v_pk_add_f32 v[50:51], v[50:51], v[54:55]
	v_pk_add_f32 v[46:47], v[48:49], v[46:47]
	s_nop 0
	v_pk_add_f32 v[46:47], v[46:47], v[50:51]
	s_nop 0
	v_add_f32_e32 v29, v46, v47
	ds_bpermute_b32 v46, v22, v29
	s_waitcnt lgkmcnt(0)
	v_add_f32_e32 v29, v29, v46
	ds_bpermute_b32 v46, v23, v29
	s_waitcnt lgkmcnt(0)
	v_add_f32_e32 v29, v29, v46
	ds_bpermute_b32 v46, v24, v29
	s_waitcnt lgkmcnt(0)
	v_add_f32_e32 v29, v29, v46
	ds_bpermute_b32 v46, v25, v29
	s_waitcnt lgkmcnt(0)
	v_add_f32_e32 v29, v29, v46
	ds_bpermute_b32 v46, v26, v29
	s_waitcnt lgkmcnt(0)
	v_add_f32_e32 v29, v29, v46
	ds_bpermute_b32 v46, v27, v29
	s_waitcnt lgkmcnt(0)
	v_add_f32_e32 v29, v29, v46
	v_fmamk_f32 v29, v29, 0x3a800000, v17
	v_mul_f32_e32 v46, 0x4f800000, v29
	v_cmp_gt_f32_e32 vcc, s3, v29
	s_nop 1
	v_cndmask_b32_e32 v29, v29, v46, vcc
	v_sqrt_f32_e32 v46, v29
	s_nop 0
	v_add_u32_e32 v47, -1, v46
	v_add_u32_e32 v48, 1, v46
	v_fma_f32 v49, -v47, v46, v29
	v_fma_f32 v50, -v48, v46, v29
	v_cmp_ge_f32_e64 s[0:1], 0, v49
	s_nop 1
	v_cndmask_b32_e64 v46, v46, v47, s[0:1]
	v_cmp_lt_f32_e64 s[0:1], 0, v50
	s_nop 1
	v_cndmask_b32_e64 v46, v46, v48, s[0:1]
	v_mul_f32_e32 v47, 0x37800000, v46
	v_cndmask_b32_e32 v46, v46, v47, vcc
	v_cmp_class_f32_e32 vcc, v29, v28
	s_nop 1
	v_cndmask_b32_e32 v29, v46, v29, vcc
	v_div_scale_f32 v46, s[0:1], v29, v29, 1.0
	v_rcp_f32_e32 v48, v46
	v_div_scale_f32 v47, vcc, 1.0, v29, 1.0
	v_fma_f32 v49, -v46, v48, 1.0
	v_fmac_f32_e32 v48, v49, v48
	v_mul_f32_e32 v49, v47, v48
	v_fma_f32 v50, -v46, v49, v47
	v_fmac_f32_e32 v49, v50, v48
	v_fma_f32 v46, -v46, v49, v47
	v_div_fmas_f32 v46, v46, v48, v49
	v_div_fixup_f32 v46, v46, v29, 1.0
	v_pk_mul_f32 v[30:31], v[30:31], v[46:47] op_sel_hi:[1,0]
	v_pk_mul_f32 v[32:33], v[32:33], v[46:47] op_sel_hi:[1,0]
	v_pk_mul_f32 v[34:35], v[34:35], v[46:47] op_sel_hi:[1,0]
	v_pk_mul_f32 v[36:37], v[36:37], v[46:47] op_sel_hi:[1,0]
	v_pk_mul_f32 v[38:39], v[38:39], v[46:47] op_sel_hi:[1,0]
	v_pk_mul_f32 v[40:41], v[40:41], v[46:47] op_sel_hi:[1,0]
	v_pk_mul_f32 v[42:43], v[42:43], v[46:47] op_sel_hi:[1,0]
	v_pk_mul_f32 v[44:45], v[44:45], v[46:47] op_sel_hi:[1,0]
	v_pk_mul_f32 v[30:31], v[12:13], v[30:31]
	v_pk_mul_f32 v[32:33], v[14:15], v[32:33]
	v_pk_mul_f32 v[34:35], v[8:9], v[34:35]
	v_pk_mul_f32 v[36:37], v[10:11], v[36:37]
	v_pk_mul_f32 v[38:39], v[4:5], v[38:39]
	v_pk_mul_f32 v[40:41], v[6:7], v[40:41]
	v_pk_mul_f32 v[42:43], v[0:1], v[42:43]
	v_pk_mul_f32 v[44:45], v[2:3], v[44:45]
	v_cvt_pk_bf16_f32 v30, v30, v31
	v_cvt_pk_bf16_f32 v31, v32, v33
	v_cvt_pk_bf16_f32 v32, v34, v35
	v_cvt_pk_bf16_f32 v33, v36, v37
	v_cvt_pk_bf16_f32 v34, v38, v39
	v_cvt_pk_bf16_f32 v35, v40, v41
	v_cvt_pk_bf16_f32 v36, v42, v43
	v_cvt_pk_bf16_f32 v37, v44, v45
	global_store_dwordx2 v[18:19], v[30:31], off offset:-1024
	global_store_dwordx2 v[18:19], v[32:33], off offset:-512
	global_store_dwordx2 v[18:19], v[34:35], off
	global_store_dwordx2 v[18:19], v[36:37], off offset:512
	v_lshl_add_u64 v[18:19], v[18:19], 0, s[6:7]
	s_waitcnt vmcnt(4)
	v_mov_b32_e32 v30, v62
	v_mov_b32_e32 v31, v63
	v_mov_b32_e32 v32, v64
	v_mov_b32_e32 v33, v65
	v_mov_b32_e32 v34, v66
	v_mov_b32_e32 v35, v67
	v_mov_b32_e32 v36, v68
	v_mov_b32_e32 v37, v69
	v_mov_b32_e32 v38, v70
	v_mov_b32_e32 v39, v71
	v_mov_b32_e32 v40, v72
	v_mov_b32_e32 v41, v73
	v_mov_b32_e32 v42, v74
	v_mov_b32_e32 v43, v75
	v_mov_b32_e32 v44, v76
	v_mov_b32_e32 v45, v77
	s_andn2_b64 exec, exec, s[14:15]
	s_cbranch_execnz .LBB0_80
